# waves 4-7 issue their LDS-DMA share right after their mid-step barrier (one stage further ahead)
# speedup vs baseline: 1.1124x; 1.0101x over previous
; DI void lds_barrier() { asm volatile("s_waitcnt lgkmcnt(0)\n\ts_barrier" ::: "memory"); }
; #define ISSUE() do { const int ka_ = (kp + koff >= nk) ? kp + koff - nk : kp + koff; \
;                 glds16x5(A + ka_ * 32, pbt + (size_t)(ka_ >> 1) * 16384 + (ka_ & 1) * 32, va, vb0, vb1, vb2, vb3, lbase + (unsigned)sp * H5_STAGE); \
;                 ++kp; if (kp == nk) { kp = 0; ++tp; pbt += (size_t)512 * K; if (tp == ntw) { tp = 0; pbt = Bt; } } sp = (sp == 2) ? 0 : sp + 1; } while (0)
; DI void run_jobs(const Params& P, int rb, int jj_lo, int jj_hi, unsigned char* smem) {
;     ...
; #pragma unroll
;                 for (int mt = 0; mt < 4; ++mt)
; #pragma unroll
;                     for (int n_ = 0; n_ < 8; ++n_) acc[mt][n_] = __builtin_amdgcn_mfma_f32_16x16x32_bf16(bfr[n_], af[mt], acc[mt][n_], 0, 0, 0);
;                 if (s + 2 < S) asm volatile("s_waitcnt vmcnt(5)" ::: "memory");
;                 else asm volatile("s_waitcnt vmcnt(0)" ::: "memory");
;                 lds_barrier();
;                 if (s + 3 < S) ISSUE();
.LBB0_144:
	s_cmp_ge_u32 s55, 0x1000
	s_cbranch_scc1 .Lg_y
	s_cmp_eq_u32 s61, 0
	s_cbranch_scc1 .Lg_plain
	s_add_i32 s21, s61, 2
	s_cmp_ge_u32 s21, s54
	s_cbranch_scc1 .Lg_plain
	s_add_i32 s8, s53, s57
	s_cmp_ge_i32 s8, s52
	s_cselect_b32 s9, s52, 0
	s_sub_i32 s21, s8, s9
	s_lshl_b32 s8, s21, 5
	s_ashr_i32 s9, s8, 31
	s_lshl_b64 s[8:9], s[8:9], 1
	s_add_u32 s8, s28, s8
	s_addc_u32 s9, s29, s9
	s_ashr_i32 s64, s21, 1
	s_ashr_i32 s65, s64, 31
	s_lshl_b64 s[64:65], s[64:65], 15
	s_add_u32 s63, s4, s64
	s_addc_u32 s65, s58, s65
	s_lshl_b32 s21, s21, 14
	s_and_b32 s21, s21, 0x4000
	s_add_u32 s64, s63, s21
	s_mul_i32 s21, s23, 0xa000
	s_addc_u32 s65, s65, 0
	s_add_i32 s21, s21, s55
	s_mov_b32 m0, s21
	s_waitcnt lgkmcnt(10)
	v_mfma_f32_16x16x32_bf16 v[124:127], v[140:143], v[172:175], v[124:127]
	s_waitcnt lgkmcnt(9)
	v_mfma_f32_16x16x32_bf16 v[120:123], v[144:147], v[172:175], v[120:123]
	s_waitcnt lgkmcnt(8)
	v_mfma_f32_16x16x32_bf16 v[116:119], v[148:151], v[172:175], v[116:119]
	s_waitcnt lgkmcnt(7)
	v_mfma_f32_16x16x32_bf16 v[112:115], v[152:155], v[172:175], v[112:115]
	s_waitcnt lgkmcnt(6)
	v_mfma_f32_16x16x32_bf16 v[108:111], v[156:159], v[172:175], v[108:111]
	s_waitcnt lgkmcnt(5)
	v_mfma_f32_16x16x32_bf16 v[104:107], v[160:163], v[172:175], v[104:107]
	s_waitcnt lgkmcnt(4)
	v_mfma_f32_16x16x32_bf16 v[100:103], v[164:167], v[172:175], v[100:103]
	s_waitcnt lgkmcnt(3)
	v_mfma_f32_16x16x32_bf16 v[96:99], v[132:135], v[172:175], v[96:99]
	global_load_lds_dwordx4 v239, s[8:9]
	s_add_u32 m0, m0, 0x2000
	s_waitcnt lgkmcnt(2)
	v_mfma_f32_16x16x32_bf16 v[92:95], v[140:143], v[168:171], v[92:95]
	v_mfma_f32_16x16x32_bf16 v[88:91], v[144:147], v[168:171], v[88:91]
	v_mfma_f32_16x16x32_bf16 v[84:87], v[148:151], v[168:171], v[84:87]
	v_mfma_f32_16x16x32_bf16 v[80:83], v[152:155], v[168:171], v[80:83]
	global_load_lds_dwordx4 v237, s[64:65]
	s_add_u32 m0, m0, 0x2000
	v_mfma_f32_16x16x32_bf16 v[76:79], v[156:159], v[168:171], v[76:79]
	v_mfma_f32_16x16x32_bf16 v[72:75], v[160:163], v[168:171], v[72:75]
	v_mfma_f32_16x16x32_bf16 v[68:71], v[164:167], v[168:171], v[68:71]
	v_mfma_f32_16x16x32_bf16 v[64:67], v[132:135], v[168:171], v[64:67]
	global_load_lds_dwordx4 v240, s[64:65]
	s_add_u32 m0, m0, 0x2000
	s_waitcnt lgkmcnt(1)
	v_mfma_f32_16x16x32_bf16 v[60:63], v[140:143], v[136:139], v[60:63]
	v_mfma_f32_16x16x32_bf16 v[56:59], v[144:147], v[136:139], v[56:59]
	v_mfma_f32_16x16x32_bf16 v[52:55], v[148:151], v[136:139], v[52:55]
	v_mfma_f32_16x16x32_bf16 v[48:51], v[152:155], v[136:139], v[48:51]
	global_load_lds_dwordx4 v238, s[64:65]
	s_add_u32 m0, m0, 0x2000
	v_mfma_f32_16x16x32_bf16 v[44:47], v[156:159], v[136:139], v[44:47]
	v_mfma_f32_16x16x32_bf16 v[40:43], v[160:163], v[136:139], v[40:43]
	v_mfma_f32_16x16x32_bf16 v[36:39], v[164:167], v[136:139], v[36:39]
	v_mfma_f32_16x16x32_bf16 v[32:35], v[132:135], v[136:139], v[32:35]
	global_load_lds_dwordx4 v241, s[64:65]
	s_waitcnt lgkmcnt(0)
	v_mfma_f32_16x16x32_bf16 v[28:31], v[140:143], v[128:131], v[28:31]
	v_mfma_f32_16x16x32_bf16 v[24:27], v[144:147], v[128:131], v[24:27]
	v_mfma_f32_16x16x32_bf16 v[20:23], v[148:151], v[128:131], v[20:23]
	v_mfma_f32_16x16x32_bf16 v[16:19], v[152:155], v[128:131], v[16:19]
	v_mfma_f32_16x16x32_bf16 v[12:15], v[156:159], v[128:131], v[12:15]
	v_mfma_f32_16x16x32_bf16 v[8:11], v[160:163], v[128:131], v[8:11]
	v_mfma_f32_16x16x32_bf16 v[4:7], v[164:167], v[128:131], v[4:7]
	v_mfma_f32_16x16x32_bf16 v[0:3], v[132:135], v[128:131], v[0:3]
	s_add_i32 s21, s53, 1
	s_cmp_eq_u32 s21, s52
	s_cselect_b64 s[8:9], -1, 0
	s_add_i32 s53, s56, 1
	s_add_u32 s63, s4, s59
	s_addc_u32 s66, s58, 0
	s_cmp_eq_u32 s53, s22
	s_cselect_b64 s[64:65], -1, 0
	s_and_b64 s[64:65], s[64:65], exec
	s_cselect_b32 s63, s94, s63
	s_cselect_b32 s64, s95, s66
	s_cselect_b32 s53, 0, s53
	s_and_b64 s[8:9], s[8:9], exec
	s_cselect_b32 s58, s64, s58
	s_cselect_b32 s4, s63, s4
	s_cselect_b32 s56, s53, s56
	s_cselect_b32 s53, 0, s21
	s_add_i32 s8, s23, 1
	s_cmp_lg_u32 s23, 2
	s_cselect_b32 s23, s8, 0
	s_waitcnt vmcnt(5)
	s_waitcnt lgkmcnt(0)
	s_barrier
	s_branch .LBB0_150

; DI void lds_barrier() { asm volatile("s_waitcnt lgkmcnt(0)\n\ts_barrier" ::: "memory"); }
; #define ISSUE() do { const int ka_ = (kp + koff >= nk) ? kp + koff - nk : kp + koff; \
;                 glds16x5(A + ka_ * 32, pbt + (size_t)(ka_ >> 1) * 16384 + (ka_ & 1) * 32, va, vb0, vb1, vb2, vb3, lbase + (unsigned)sp * H5_STAGE); \
;                 ++kp; if (kp == nk) { kp = 0; ++tp; pbt += (size_t)512 * K; if (tp == ntw) { tp = 0; pbt = Bt; } } sp = (sp == 2) ? 0 : sp + 1; } while (0)
; DI void run_jobs(const Params& P, int rb, int jj_lo, int jj_hi, unsigned char* smem) {
;     ...
; #pragma unroll
;                 for (int mt = 0; mt < 4; ++mt)
; #pragma unroll
;                     for (int n_ = 0; n_ < 8; ++n_) acc[mt][n_] = __builtin_amdgcn_mfma_f32_16x16x32_bf16(bfr[n_], af[mt], acc[mt][n_], 0, 0, 0);
;                 if (s + 2 < S) asm volatile("s_waitcnt vmcnt(5)" ::: "memory");
;                 else asm volatile("s_waitcnt vmcnt(0)" ::: "memory");
;                 lds_barrier();
;                 if (s + 3 < S) ISSUE();
.Lg_y:
	s_nop 0
	s_add_i32 s21, s61, 3
	s_cmp_ge_u32 s21, s54
	s_cbranch_scc1 .Lg_y_plain
	s_add_i32 s8, s53, s57
	s_cmp_ge_i32 s8, s52
	s_cselect_b32 s9, s52, 0
	s_sub_i32 s21, s8, s9
	s_lshl_b32 s8, s21, 5
	s_ashr_i32 s9, s8, 31
	s_lshl_b64 s[8:9], s[8:9], 1
	s_add_u32 s8, s28, s8
	s_addc_u32 s9, s29, s9
	s_ashr_i32 s64, s21, 1
	s_ashr_i32 s65, s64, 31
	s_lshl_b64 s[64:65], s[64:65], 15
	s_add_u32 s63, s4, s64
	s_addc_u32 s65, s58, s65
	s_lshl_b32 s21, s21, 14
	s_and_b32 s21, s21, 0x4000
	s_add_u32 s64, s63, s21
	s_mul_i32 s21, s23, 0xa000
	s_addc_u32 s65, s65, 0
	s_add_i32 s21, s21, s55
	s_mov_b32 m0, s21
	s_waitcnt lgkmcnt(10)
	v_mfma_f32_16x16x32_bf16 v[124:127], v[140:143], v[172:175], v[124:127]
	s_waitcnt lgkmcnt(9)
	v_mfma_f32_16x16x32_bf16 v[120:123], v[144:147], v[172:175], v[120:123]
	s_waitcnt lgkmcnt(8)
	v_mfma_f32_16x16x32_bf16 v[116:119], v[148:151], v[172:175], v[116:119]
	s_waitcnt lgkmcnt(7)
	v_mfma_f32_16x16x32_bf16 v[112:115], v[152:155], v[172:175], v[112:115]
	s_waitcnt lgkmcnt(6)
	v_mfma_f32_16x16x32_bf16 v[108:111], v[156:159], v[172:175], v[108:111]
	s_waitcnt lgkmcnt(5)
	v_mfma_f32_16x16x32_bf16 v[104:107], v[160:163], v[172:175], v[104:107]
	s_waitcnt lgkmcnt(4)
	v_mfma_f32_16x16x32_bf16 v[100:103], v[164:167], v[172:175], v[100:103]
	s_waitcnt lgkmcnt(3)
	v_mfma_f32_16x16x32_bf16 v[96:99], v[132:135], v[172:175], v[96:99]
	s_waitcnt lgkmcnt(2)
	v_mfma_f32_16x16x32_bf16 v[92:95], v[140:143], v[168:171], v[92:95]
	v_mfma_f32_16x16x32_bf16 v[88:91], v[144:147], v[168:171], v[88:91]
	v_mfma_f32_16x16x32_bf16 v[84:87], v[148:151], v[168:171], v[84:87]
	v_mfma_f32_16x16x32_bf16 v[80:83], v[152:155], v[168:171], v[80:83]
	v_mfma_f32_16x16x32_bf16 v[76:79], v[156:159], v[168:171], v[76:79]
	v_mfma_f32_16x16x32_bf16 v[72:75], v[160:163], v[168:171], v[72:75]
	v_mfma_f32_16x16x32_bf16 v[68:71], v[164:167], v[168:171], v[68:71]
	v_mfma_f32_16x16x32_bf16 v[64:67], v[132:135], v[168:171], v[64:67]
	s_waitcnt vmcnt(5)
	s_waitcnt lgkmcnt(0)
	s_barrier
	s_waitcnt lgkmcnt(1)
	v_mfma_f32_16x16x32_bf16 v[60:63], v[140:143], v[136:139], v[60:63]
	global_load_lds_dwordx4 v239, s[8:9]
	s_add_u32 m0, m0, 0x2000
	v_mfma_f32_16x16x32_bf16 v[56:59], v[144:147], v[136:139], v[56:59]
	v_mfma_f32_16x16x32_bf16 v[52:55], v[148:151], v[136:139], v[52:55]
	global_load_lds_dwordx4 v237, s[64:65]
	s_add_u32 m0, m0, 0x2000
	v_mfma_f32_16x16x32_bf16 v[48:51], v[152:155], v[136:139], v[48:51]
	v_mfma_f32_16x16x32_bf16 v[44:47], v[156:159], v[136:139], v[44:47]
	global_load_lds_dwordx4 v240, s[64:65]
	s_add_u32 m0, m0, 0x2000
	v_mfma_f32_16x16x32_bf16 v[40:43], v[160:163], v[136:139], v[40:43]
	v_mfma_f32_16x16x32_bf16 v[36:39], v[164:167], v[136:139], v[36:39]
	global_load_lds_dwordx4 v238, s[64:65]
	s_add_u32 m0, m0, 0x2000
	v_mfma_f32_16x16x32_bf16 v[32:35], v[132:135], v[136:139], v[32:35]
	s_waitcnt lgkmcnt(0)
	v_mfma_f32_16x16x32_bf16 v[28:31], v[140:143], v[128:131], v[28:31]
	global_load_lds_dwordx4 v241, s[64:65]
	v_mfma_f32_16x16x32_bf16 v[24:27], v[144:147], v[128:131], v[24:27]
	v_mfma_f32_16x16x32_bf16 v[20:23], v[148:151], v[128:131], v[20:23]
	v_mfma_f32_16x16x32_bf16 v[16:19], v[152:155], v[128:131], v[16:19]
	v_mfma_f32_16x16x32_bf16 v[12:15], v[156:159], v[128:131], v[12:15]
	v_mfma_f32_16x16x32_bf16 v[8:11], v[160:163], v[128:131], v[8:11]
	v_mfma_f32_16x16x32_bf16 v[4:7], v[164:167], v[128:131], v[4:7]
	v_mfma_f32_16x16x32_bf16 v[0:3], v[132:135], v[128:131], v[0:3]
	s_add_i32 s21, s53, 1
	s_cmp_eq_u32 s21, s52
	s_cselect_b64 s[8:9], -1, 0
	s_add_i32 s53, s56, 1
	s_add_u32 s63, s4, s59
	s_addc_u32 s66, s58, 0
	s_cmp_eq_u32 s53, s22
	s_cselect_b64 s[64:65], -1, 0
	s_and_b64 s[64:65], s[64:65], exec
	s_cselect_b32 s63, s94, s63
	s_cselect_b32 s64, s95, s66
	s_cselect_b32 s53, 0, s53
	s_and_b64 s[8:9], s[8:9], exec
	s_cselect_b32 s58, s64, s58
	s_cselect_b32 s4, s63, s4
	s_cselect_b32 s56, s53, s56
	s_cselect_b32 s53, 0, s21
	s_add_i32 s8, s23, 1
	s_cmp_lg_u32 s23, 2
	s_cselect_b32 s23, s8, 0
	s_branch .LBB0_150
.Lg_y_plain:
	s_waitcnt lgkmcnt(10)
	v_mfma_f32_16x16x32_bf16 v[124:127], v[140:143], v[172:175], v[124:127]
	s_waitcnt lgkmcnt(9)
	v_mfma_f32_16x16x32_bf16 v[120:123], v[144:147], v[172:175], v[120:123]
	s_waitcnt lgkmcnt(8)
	v_mfma_f32_16x16x32_bf16 v[116:119], v[148:151], v[172:175], v[116:119]
	s_waitcnt lgkmcnt(7)
	v_mfma_f32_16x16x32_bf16 v[112:115], v[152:155], v[172:175], v[112:115]
	s_waitcnt lgkmcnt(6)
	v_mfma_f32_16x16x32_bf16 v[108:111], v[156:159], v[172:175], v[108:111]
	s_waitcnt lgkmcnt(5)
	v_mfma_f32_16x16x32_bf16 v[104:107], v[160:163], v[172:175], v[104:107]
	s_waitcnt lgkmcnt(4)
	v_mfma_f32_16x16x32_bf16 v[100:103], v[164:167], v[172:175], v[100:103]
	s_waitcnt lgkmcnt(3)
	v_mfma_f32_16x16x32_bf16 v[96:99], v[132:135], v[172:175], v[96:99]
	s_waitcnt lgkmcnt(2)
	v_mfma_f32_16x16x32_bf16 v[92:95], v[140:143], v[168:171], v[92:95]
	v_mfma_f32_16x16x32_bf16 v[88:91], v[144:147], v[168:171], v[88:91]
	v_mfma_f32_16x16x32_bf16 v[84:87], v[148:151], v[168:171], v[84:87]
	v_mfma_f32_16x16x32_bf16 v[80:83], v[152:155], v[168:171], v[80:83]
	v_mfma_f32_16x16x32_bf16 v[76:79], v[156:159], v[168:171], v[76:79]
	v_mfma_f32_16x16x32_bf16 v[72:75], v[160:163], v[168:171], v[72:75]
	v_mfma_f32_16x16x32_bf16 v[68:71], v[164:167], v[168:171], v[68:71]
	v_mfma_f32_16x16x32_bf16 v[64:67], v[132:135], v[168:171], v[64:67]
	s_add_i32 s21, s61, 2
	s_cmp_ge_u32 s21, s54
	s_cbranch_scc1 .Lg_drain_y
	s_waitcnt vmcnt(5)
	s_branch .Lg_bar_y
